# grid barrier: waiting workgroups watch the cross-XCD release word directly instead of the per-XCD word their leader relays it to
# baseline (speedup 1.0000x reference)
.LBB0_137:
	s_or_b64 exec, exec, s[12:13]
	v_cvt_f32_u32_e32 v5, v3
	s_waitcnt vmcnt(0)
	v_readfirstlane_b32 s3, v4
	v_sub_u32_e32 v4, 0, v3
	v_rcp_iflag_f32_e32 v5, v5
	v_add_u32_e32 v6, s3, v2
	v_mul_f32_e32 v5, 0x4f7ffffe, v5
	v_cvt_u32_f32_e32 v5, v5
	v_mul_lo_u32 v2, v4, v5
	v_mul_hi_u32 v2, v5, v2
	v_add_u32_e32 v2, v5, v2
	v_mul_hi_u32 v2, v6, v2
	v_mul_lo_u32 v4, v2, v3
	v_sub_u32_e32 v4, v6, v4
	v_add_u32_e32 v5, 1, v2
	v_cmp_ge_u32_e32 vcc, v4, v3
	s_nop 1
	v_cndmask_b32_e32 v2, v2, v5, vcc
	v_sub_u32_e32 v5, v4, v3
	v_cndmask_b32_e32 v4, v4, v5, vcc
	v_add_u32_e32 v5, 1, v2
	v_cmp_ge_u32_e32 vcc, v4, v3
	v_add_u32_e32 v4, 1, v6
	s_nop 0
	v_cndmask_b32_e32 v2, v2, v5, vcc
	v_mul_lo_u32 v5, v3, v2
	v_add_u32_e32 v3, v5, v3
	v_cmp_ne_u32_e32 vcc, v4, v3
	s_and_saveexec_b64 s[4:5], vcc
	s_xor_b64 s[10:11], exec, s[4:5]
	s_cbranch_execz .LBB0_151
	s_waitcnt lgkmcnt(0)
	s_add_u32 s16, s72, 0x7500
	s_addc_u32 s17, s73, 0
	v_mov_b32_e32 v1, 0
	global_load_dword v1, v1, s[16:17] sc1
	s_waitcnt vmcnt(0)
	v_cmp_eq_u32_e32 vcc, v1, v2
	s_and_saveexec_b64 s[12:13], vcc
	s_cbranch_execz .LBB0_150
	s_add_u32 s14, s72, 0x4200
	s_addc_u32 s15, s73, 0
	s_mov_b32 s3, 1
	s_mov_b64 s[18:19], 0
	v_mov_b32_e32 v1, 0
	s_branch .LBB0_141

.LBB0_283:
	s_or_b64 exec, exec, s[10:11]
	v_cvt_f32_u32_e32 v5, v3
	s_waitcnt vmcnt(0)
	v_readfirstlane_b32 s3, v4
	v_sub_u32_e32 v4, 0, v3
	v_rcp_iflag_f32_e32 v5, v5
	v_add_u32_e32 v6, s3, v2
	v_mul_f32_e32 v5, 0x4f7ffffe, v5
	v_cvt_u32_f32_e32 v5, v5
	v_mul_lo_u32 v2, v4, v5
	v_mul_hi_u32 v2, v5, v2
	v_add_u32_e32 v2, v5, v2
	v_mul_hi_u32 v2, v6, v2
	v_mul_lo_u32 v4, v2, v3
	v_sub_u32_e32 v4, v6, v4
	v_add_u32_e32 v5, 1, v2
	v_cmp_ge_u32_e32 vcc, v4, v3
	s_nop 1
	v_cndmask_b32_e32 v2, v2, v5, vcc
	v_sub_u32_e32 v5, v4, v3
	v_cndmask_b32_e32 v4, v4, v5, vcc
	v_add_u32_e32 v5, 1, v2
	v_cmp_ge_u32_e32 vcc, v4, v3
	v_add_u32_e32 v4, 1, v6
	s_nop 0
	v_cndmask_b32_e32 v2, v2, v5, vcc
	v_mul_lo_u32 v5, v3, v2
	v_add_u32_e32 v3, v5, v3
	v_cmp_ne_u32_e32 vcc, v4, v3
	s_and_saveexec_b64 s[4:5], vcc
	s_xor_b64 s[8:9], exec, s[4:5]
	s_cbranch_execz .LBB0_297
	s_waitcnt lgkmcnt(0)
	s_add_u32 s16, s72, 0x7500
	s_addc_u32 s17, s73, 0
	v_mov_b32_e32 v1, 0
	global_load_dword v1, v1, s[16:17] sc1
	s_waitcnt vmcnt(0)
	v_cmp_eq_u32_e32 vcc, v1, v2
	s_and_saveexec_b64 s[10:11], vcc
	s_cbranch_execz .LBB0_296
	s_add_u32 s12, s72, 0x4200
	s_addc_u32 s13, s73, 0
	s_mov_b32 s3, 1
	s_mov_b64 s[18:19], 0
	v_mov_b32_e32 v1, 0
	s_branch .LBB0_287

.LBB0_476:
	s_or_b64 exec, exec, s[14:15]
	v_cvt_f32_u32_e32 v5, v3
	s_waitcnt vmcnt(0)
	v_readfirstlane_b32 s3, v4
	v_sub_u32_e32 v4, 0, v3
	v_rcp_iflag_f32_e32 v5, v5
	v_add_u32_e32 v6, s3, v2
	v_mul_f32_e32 v5, 0x4f7ffffe, v5
	v_cvt_u32_f32_e32 v5, v5
	v_mul_lo_u32 v2, v4, v5
	v_mul_hi_u32 v2, v5, v2
	v_add_u32_e32 v2, v5, v2
	v_mul_hi_u32 v2, v6, v2
	v_mul_lo_u32 v4, v2, v3
	v_sub_u32_e32 v4, v6, v4
	v_add_u32_e32 v5, 1, v2
	v_cmp_ge_u32_e32 vcc, v4, v3
	s_nop 1
	v_cndmask_b32_e32 v2, v2, v5, vcc
	v_sub_u32_e32 v5, v4, v3
	v_cndmask_b32_e32 v4, v4, v5, vcc
	v_add_u32_e32 v5, 1, v2
	v_cmp_ge_u32_e32 vcc, v4, v3
	v_add_u32_e32 v4, 1, v6
	s_nop 0
	v_cndmask_b32_e32 v2, v2, v5, vcc
	v_mul_lo_u32 v5, v3, v2
	v_add_u32_e32 v3, v5, v3
	v_cmp_ne_u32_e32 vcc, v4, v3
	s_and_saveexec_b64 s[4:5], vcc
	s_xor_b64 s[12:13], exec, s[4:5]
	s_cbranch_execz .LBB0_490
	s_waitcnt lgkmcnt(0)
	s_add_u32 s18, s72, 0x7500
	s_addc_u32 s19, s73, 0
	v_mov_b32_e32 v1, 0
	global_load_dword v1, v1, s[18:19] sc1
	s_waitcnt vmcnt(0)
	v_cmp_eq_u32_e32 vcc, v1, v2
	s_and_saveexec_b64 s[14:15], vcc
	s_cbranch_execz .LBB0_489
	s_add_u32 s16, s72, 0x4200
	s_addc_u32 s17, s73, 0
	s_mov_b32 s3, 1
	s_mov_b64 s[20:21], 0
	v_mov_b32_e32 v1, 0
	s_branch .LBB0_480

.LBB0_738:
	s_or_b64 exec, exec, s[12:13]
	v_cvt_f32_u32_e32 v5, v3
	s_waitcnt vmcnt(0)
	v_readfirstlane_b32 s3, v4
	v_sub_u32_e32 v4, 0, v3
	v_rcp_iflag_f32_e32 v5, v5
	v_add_u32_e32 v6, s3, v2
	v_mul_f32_e32 v5, 0x4f7ffffe, v5
	v_cvt_u32_f32_e32 v5, v5
	v_mul_lo_u32 v2, v4, v5
	v_mul_hi_u32 v2, v5, v2
	v_add_u32_e32 v2, v5, v2
	v_mul_hi_u32 v2, v6, v2
	v_mul_lo_u32 v4, v2, v3
	v_sub_u32_e32 v4, v6, v4
	v_add_u32_e32 v5, 1, v2
	v_cmp_ge_u32_e32 vcc, v4, v3
	s_nop 1
	v_cndmask_b32_e32 v2, v2, v5, vcc
	v_sub_u32_e32 v5, v4, v3
	v_cndmask_b32_e32 v4, v4, v5, vcc
	v_add_u32_e32 v5, 1, v2
	v_cmp_ge_u32_e32 vcc, v4, v3
	v_add_u32_e32 v4, 1, v6
	s_nop 0
	v_cndmask_b32_e32 v2, v2, v5, vcc
	v_mul_lo_u32 v5, v3, v2
	v_add_u32_e32 v3, v5, v3
	v_cmp_ne_u32_e32 vcc, v4, v3
	s_and_saveexec_b64 s[4:5], vcc
	s_xor_b64 s[10:11], exec, s[4:5]
	s_cbranch_execz .LBB0_752
	s_waitcnt lgkmcnt(0)
	s_add_u32 s16, s72, 0x7500
	s_addc_u32 s17, s73, 0
	v_mov_b32_e32 v1, 0
	global_load_dword v1, v1, s[16:17] sc1
	s_waitcnt vmcnt(0)
	v_cmp_eq_u32_e32 vcc, v1, v2
	s_and_saveexec_b64 s[12:13], vcc
	s_cbranch_execz .LBB0_751
	s_add_u32 s14, s72, 0x4200
	s_addc_u32 s15, s73, 0
	s_mov_b32 s3, 1
	s_mov_b64 s[20:21], 0
	v_mov_b32_e32 v1, 0
	s_branch .LBB0_742

.LBB0_1612:
	s_or_b64 exec, exec, s[12:13]
	v_cvt_f32_u32_e32 v4, v2
	s_waitcnt vmcnt(0)
	v_readfirstlane_b32 s3, v3
	v_sub_u32_e32 v3, 0, v2
	v_rcp_iflag_f32_e32 v4, v4
	v_add_u32_e32 v5, s3, v1
	v_mul_f32_e32 v4, 0x4f7ffffe, v4
	v_cvt_u32_f32_e32 v4, v4
	v_mul_lo_u32 v1, v3, v4
	v_mul_hi_u32 v1, v4, v1
	v_add_u32_e32 v1, v4, v1
	v_mul_hi_u32 v1, v5, v1
	v_mul_lo_u32 v3, v1, v2
	v_sub_u32_e32 v3, v5, v3
	v_add_u32_e32 v4, 1, v1
	v_cmp_ge_u32_e32 vcc, v3, v2
	s_nop 1
	v_cndmask_b32_e32 v1, v1, v4, vcc
	v_sub_u32_e32 v4, v3, v2
	v_cndmask_b32_e32 v3, v3, v4, vcc
	v_add_u32_e32 v4, 1, v1
	v_cmp_ge_u32_e32 vcc, v3, v2
	v_add_u32_e32 v3, 1, v5
	s_nop 0
	v_cndmask_b32_e32 v1, v1, v4, vcc
	v_mul_lo_u32 v4, v2, v1
	v_add_u32_e32 v2, v4, v2
	v_cmp_ne_u32_e32 vcc, v3, v2
	s_and_saveexec_b64 s[4:5], vcc
	s_xor_b64 s[10:11], exec, s[4:5]
	s_cbranch_execz .LBB0_1626
	s_waitcnt lgkmcnt(0)
	s_add_u32 s16, s72, 0x7500
	s_addc_u32 s17, s73, 0
	v_mov_b32_e32 v0, 0
	global_load_dword v0, v0, s[16:17] sc1
	s_waitcnt vmcnt(0)
	v_cmp_eq_u32_e32 vcc, v0, v1
	s_and_saveexec_b64 s[12:13], vcc
	s_cbranch_execz .LBB0_1625
	s_add_u32 s14, s72, 0x4200
	s_addc_u32 s15, s73, 0
	s_mov_b32 s3, 1
	s_mov_b64 s[18:19], 0
	v_mov_b32_e32 v0, 0
	s_branch .LBB0_1616

.LBB0_1722:
	s_or_b64 exec, exec, s[14:15]
	v_cvt_f32_u32_e32 v4, v2
	s_waitcnt vmcnt(0)
	v_readfirstlane_b32 s3, v3
	v_sub_u32_e32 v3, 0, v2
	v_rcp_iflag_f32_e32 v4, v4
	v_add_u32_e32 v5, s3, v1
	v_mul_f32_e32 v4, 0x4f7ffffe, v4
	v_cvt_u32_f32_e32 v4, v4
	v_mul_lo_u32 v1, v3, v4
	v_mul_hi_u32 v1, v4, v1
	v_add_u32_e32 v1, v4, v1
	v_mul_hi_u32 v1, v5, v1
	v_mul_lo_u32 v3, v1, v2
	v_sub_u32_e32 v3, v5, v3
	v_add_u32_e32 v4, 1, v1
	v_cmp_ge_u32_e32 vcc, v3, v2
	s_nop 1
	v_cndmask_b32_e32 v1, v1, v4, vcc
	v_sub_u32_e32 v4, v3, v2
	v_cndmask_b32_e32 v3, v3, v4, vcc
	v_add_u32_e32 v4, 1, v1
	v_cmp_ge_u32_e32 vcc, v3, v2
	v_add_u32_e32 v3, 1, v5
	s_nop 0
	v_cndmask_b32_e32 v1, v1, v4, vcc
	v_mul_lo_u32 v4, v2, v1
	v_add_u32_e32 v2, v4, v2
	v_cmp_ne_u32_e32 vcc, v3, v2
	s_and_saveexec_b64 s[4:5], vcc
	s_xor_b64 s[12:13], exec, s[4:5]
	s_cbranch_execz .LBB0_1736
	s_waitcnt lgkmcnt(0)
	s_add_u32 s18, s72, 0x7500
	s_addc_u32 s19, s73, 0
	v_mov_b32_e32 v0, 0
	global_load_dword v0, v0, s[18:19] sc1
	s_waitcnt vmcnt(0)
	v_cmp_eq_u32_e32 vcc, v0, v1
	s_and_saveexec_b64 s[14:15], vcc
	s_cbranch_execz .LBB0_1735
	s_add_u32 s16, s72, 0x4200
	s_addc_u32 s17, s73, 0
	s_mov_b32 s3, 1
	s_mov_b64 s[20:21], 0
	v_mov_b32_e32 v0, 0
	s_branch .LBB0_1726

.LBB0_1847:
	s_or_b64 exec, exec, s[12:13]
	v_cvt_f32_u32_e32 v4, v2
	s_waitcnt vmcnt(0)
	v_readfirstlane_b32 s3, v3
	v_sub_u32_e32 v3, 0, v2
	v_rcp_iflag_f32_e32 v4, v4
	v_add_u32_e32 v5, s3, v1
	v_mul_f32_e32 v4, 0x4f7ffffe, v4
	v_cvt_u32_f32_e32 v4, v4
	v_mul_lo_u32 v1, v3, v4
	v_mul_hi_u32 v1, v4, v1
	v_add_u32_e32 v1, v4, v1
	v_mul_hi_u32 v1, v5, v1
	v_mul_lo_u32 v3, v1, v2
	v_sub_u32_e32 v3, v5, v3
	v_add_u32_e32 v4, 1, v1
	v_cmp_ge_u32_e32 vcc, v3, v2
	s_nop 1
	v_cndmask_b32_e32 v1, v1, v4, vcc
	v_sub_u32_e32 v4, v3, v2
	v_cndmask_b32_e32 v3, v3, v4, vcc
	v_add_u32_e32 v4, 1, v1
	v_cmp_ge_u32_e32 vcc, v3, v2
	v_add_u32_e32 v3, 1, v5
	s_nop 0
	v_cndmask_b32_e32 v1, v1, v4, vcc
	v_mul_lo_u32 v4, v2, v1
	v_add_u32_e32 v2, v4, v2
	v_cmp_ne_u32_e32 vcc, v3, v2
	s_and_saveexec_b64 s[4:5], vcc
	s_xor_b64 s[10:11], exec, s[4:5]
	s_cbranch_execz .LBB0_1861
	s_waitcnt lgkmcnt(0)
	s_add_u32 s16, s72, 0x7500
	s_addc_u32 s17, s73, 0
	v_mov_b32_e32 v0, 0
	global_load_dword v0, v0, s[16:17] sc1
	s_waitcnt vmcnt(0)
	v_cmp_eq_u32_e32 vcc, v0, v1
	s_and_saveexec_b64 s[12:13], vcc
	s_cbranch_execz .LBB0_1860
	s_add_u32 s14, s72, 0x4200
	s_addc_u32 s15, s73, 0
	s_mov_b32 s3, 1
	s_mov_b64 s[20:21], 0
	v_mov_b32_e32 v0, 0
	s_branch .LBB0_1851

.LBB0_1963:
	s_or_b64 exec, exec, s[20:21]
	v_cvt_f32_u32_e32 v4, v2
	s_waitcnt vmcnt(0)
	v_readfirstlane_b32 s3, v3
	v_sub_u32_e32 v3, 0, v2
	v_rcp_iflag_f32_e32 v4, v4
	v_add_u32_e32 v5, s3, v1
	v_mul_f32_e32 v4, 0x4f7ffffe, v4
	v_cvt_u32_f32_e32 v4, v4
	v_mul_lo_u32 v1, v3, v4
	v_mul_hi_u32 v1, v4, v1
	v_add_u32_e32 v1, v4, v1
	v_mul_hi_u32 v1, v5, v1
	v_mul_lo_u32 v3, v1, v2
	v_sub_u32_e32 v3, v5, v3
	v_add_u32_e32 v4, 1, v1
	v_cmp_ge_u32_e32 vcc, v3, v2
	s_nop 1
	v_cndmask_b32_e32 v1, v1, v4, vcc
	v_sub_u32_e32 v4, v3, v2
	v_cndmask_b32_e32 v3, v3, v4, vcc
	v_add_u32_e32 v4, 1, v1
	v_cmp_ge_u32_e32 vcc, v3, v2
	v_add_u32_e32 v3, 1, v5
	s_nop 0
	v_cndmask_b32_e32 v1, v1, v4, vcc
	v_mul_lo_u32 v4, v2, v1
	v_add_u32_e32 v2, v4, v2
	v_cmp_ne_u32_e32 vcc, v3, v2
	s_and_saveexec_b64 s[16:17], vcc
	s_xor_b64 s[16:17], exec, s[16:17]
	s_cbranch_execz .LBB0_1977
	s_waitcnt lgkmcnt(0)
	s_add_u32 s26, s72, 0x7500
	s_addc_u32 s27, s73, 0
	v_mov_b32_e32 v0, 0
	global_load_dword v0, v0, s[26:27] sc1
	s_waitcnt vmcnt(0)
	v_cmp_eq_u32_e32 vcc, v0, v1
	s_and_saveexec_b64 s[20:21], vcc
	s_cbranch_execz .LBB0_1976
	s_add_u32 s24, s72, 0x4200
	s_addc_u32 s25, s73, 0
	s_mov_b32 s3, 1
	s_mov_b64 s[28:29], 0
	v_mov_b32_e32 v0, 0
	s_branch .LBB0_1967
